# DK32 attention: both folds, exp hoisted before PV MFMA pairs instead of s_nop pads, two-chain row max
# speedup vs baseline: 1.0333x; 1.0027x over previous
; template <int DK>
; DI void attn_item(const Params& p, int layer, int b, int hd, int qt, int ctxq, char* smem) {
;     ...
;     for (int kt = 0; kt < nkt; ++kt) {
;         const int cur = kt & 1;
;         const bf16_t* kb_ = sK + cur * 64 * 72; const bf16_t* vb_ = sV + cur * 64 * 68;
; #pragma unroll
;         for (int s = 0; s < 2; ++s) {
;             if (s == 1) {
;                 if (kt + 1 < nkt) {
; #pragma unroll
;                     for (int i = 0; i < 2; ++i) { rk[i] = *(const u32x4*)(Kg + (size_t)((kt + 1) * 64 + srow + 32 * i) * 64 + sc8); rv[i] = *(const u32x4*)(Vg + (size_t)(srow + 32 * i) * NKEY + (kt + 1) * 64 + sc8); }
;                 }
;             }
;             f32x16 x[2];
; #pragma unroll
;             for (int kb = 0; kb < 2; ++kb)
; #pragma unroll
;                 for (int i = 0; i < 16; ++i) x[kb][i] = 0.f;
;             const int kofs = DK == 32 ? 32 * s : 0;
; #pragma unroll
;             for (int ks = 0; ks < NKS; ++ks) {
;                 const bf16x8 a0 = *(const bf16x8*)(kb_ + r * 72 + kofs + 16 * ks + 8 * h), a1 = *(const bf16x8*)(kb_ + (32 + r) * 72 + kofs + 16 * ks + 8 * h);
;                 const bf16x8 qv = *(const bf16x8*)(sQ + ((s * NKS + ks) * 64 + lane) * 8);
;                 x[0] = MFMA32(a0, qv, x[0]); x[1] = MFMA32(a1, qv, x[1]);
;             }
;             float mx = x[0][0];
; #pragma unroll
;             for (int i = 1; i < 16; ++i) mx = fmaxf(mx, x[0][i]);
; #pragma unroll
;             for (int i = 0; i < 16; ++i) mx = fmaxf(mx, x[1][i]);
;             mx = fmaxf(mx, shx(mx, lane, 32));
;             if (__builtin_amdgcn_ballot_w64(mx > m_[s] + 8.f) != 0) {
;                 const float mn = fmaxf(m_[s], mx);
;                 const float al = __builtin_amdgcn_exp2f(m_[s] - mn);
;                 m_[s] = mn;
;                 l_[s] *= al;
; #pragma unroll
;                 for (int d = 0; d < 2; ++d)
; #pragma unroll
;                     for (int i = 0; i < 16; ++i) O[s][d][i] *= al;
;             }
;             const f32x2 mref = {m_[s], m_[s]};
;             float ps = 0.f;
; #pragma unroll
;             for (int kb = 0; kb < 2; ++kb)
; #pragma unroll
;                 for (int i2 = 0; i2 < 8; ++i2) {
;                     f32x2 t = {x[kb][2 * i2], x[kb][2 * i2 + 1]};
;                     asm("v_pk_add_f32 %0, %1, %2 neg_lo:[0,1] neg_hi:[0,1]" : "=v"(t) : "v"(t), "v"(mref));
.LBB0_158:
	s_mov_b32 s8, 0
	ds_read_b128 v[222:225], v171 offset:35840
	ds_read_b128 v[240:243], v171 offset:36864
	ds_read_b128 v[244:247], v171 offset:37888
	ds_read_b128 v[248:251], v171 offset:38912
	ds_read_b128 v[128:131], v149
	ds_read_b128 v[132:135], v149 offset:4608
	ds_read_b128 v[136:139], v149 offset:32
	ds_read_b128 v[140:143], v149 offset:4640
	v_lshl_add_u64 v[226:227], v[154:155], 0, v[160:161]
	s_mov_b64 s[10:11], 0x84000
	v_lshl_add_u64 v[236:237], v[226:227], 0, s[10:11]
	v_lshl_add_u64 v[230:231], v[156:157], 0, v[160:161]
	s_mov_b64 s[10:11], 0x3000
	v_lshl_add_u64 v[230:231], v[230:231], 0, s[10:11]
	global_load_dwordx4 v[206:209], v[230:231], off offset:-4096
	global_load_dwordx4 v[210:213], v[230:231], off
	global_load_dwordx4 v[214:217], v[226:227], off offset:128
	global_load_dwordx4 v[218:221], v[236:237], off offset:128
	v_mov_b32_e32 v153, v152
	v_mov_b32_e32 v147, v146
	s_and_b32 s9, s8, 1
	s_mul_i32 s10, s9, 0x2400
	s_mul_i32 s11, s9, 0x2200
	v_add_u32_e32 v173, s10, v149
	v_add_u32_e32 v236, s11, v172
	v_add_u32_e32 v237, 0x5800, v236
	v_add_u32_e32 v236, 0x4800, v236
	s_waitcnt lgkmcnt(0)
	v_mfma_f32_32x32x16_bf16 v[80:95], v[128:131], v[222:225], 0
	v_mfma_f32_32x32x16_bf16 v[80:95], v[136:139], v[240:243], v[80:95]
	v_mfma_f32_32x32x16_bf16 v[64:79], v[132:135], v[222:225], 0
	v_mfma_f32_32x32x16_bf16 v[64:79], v[140:143], v[240:243], v[64:79]
	ds_read2_b64 v[96:99], v236 offset0:0 offset1:2
	ds_read2_b64 v[112:115], v237 offset0:32 offset1:34
	ds_read2_b64 v[100:103], v236 offset0:4 offset1:6
	ds_read2_b64 v[116:119], v237 offset0:36 offset1:38
	ds_read2_b64 v[104:107], v236 offset0:8 offset1:10
	ds_read2_b64 v[120:123], v237 offset0:40 offset1:42
	ds_read2_b64 v[108:111], v236 offset0:12 offset1:14
	ds_read2_b64 v[124:127], v237 offset0:44 offset1:46
	ds_read_b128 v[128:131], v173 offset:64
	ds_read_b128 v[132:135], v173 offset:4672
	ds_read_b128 v[136:139], v173 offset:96
	ds_read_b128 v[140:143], v173 offset:4704
	v_max3_f32 v233, v80, v81, v82
	v_max3_f32 v233, v233, v83, v84
	v_max3_f32 v233, v233, v85, v86
	v_max3_f32 v233, v233, v87, v88
	v_max3_f32 v233, v233, v89, v90
	v_max3_f32 v233, v233, v91, v92
	v_max3_f32 v233, v233, v93, v94
	v_max3_f32 v234, v64, v65, v66
	v_max_f32_e32 v233, v233, v95
	v_max3_f32 v234, v234, v67, v68
	v_max3_f32 v234, v234, v69, v70
	v_max3_f32 v234, v234, v71, v72
	v_max3_f32 v234, v234, v73, v74
	v_max3_f32 v234, v234, v75, v76
	v_max3_f32 v234, v234, v77, v78
	v_max3_f32 v233, v233, v234, v79
	v_mov_b32_e32 v234, v233
	s_nop 1
	v_permlane32_swap_b32_e32 v234, v233
	s_nop 0
	v_max_f32_e32 v233, v233, v234
	v_add_f32_e32 v234, 0x41000000, v152
	v_cmp_gt_f32_e32 vcc, v233, v234
	s_cbranch_vccz .Lat32_nors0f
	v_max_f32_e32 v239, v152, v233
	v_sub_f32_e32 v234, v152, v239
	v_exp_f32_e32 v234, v234
	v_mov_b32_e32 v152, v239
	v_mov_b32_e32 v153, v239
	v_mul_f32_e32 v151, v151, v234
	v_mul_f32_e32 v32, v32, v234
	v_mul_f32_e32 v33, v33, v234
	v_mul_f32_e32 v34, v34, v234
	v_mul_f32_e32 v35, v35, v234
	v_mul_f32_e32 v36, v36, v234
	v_mul_f32_e32 v37, v37, v234
	v_mul_f32_e32 v38, v38, v234
	v_mul_f32_e32 v39, v39, v234
	v_mul_f32_e32 v40, v40, v234
	v_mul_f32_e32 v41, v41, v234
	v_mul_f32_e32 v42, v42, v234
	v_mul_f32_e32 v43, v43, v234
	v_mul_f32_e32 v44, v44, v234
	v_mul_f32_e32 v45, v45, v234
	v_mul_f32_e32 v46, v46, v234
	v_mul_f32_e32 v47, v47, v234
	v_mul_f32_e32 v0, v0, v234
	v_mul_f32_e32 v1, v1, v234
	v_mul_f32_e32 v2, v2, v234
	v_mul_f32_e32 v3, v3, v234
	v_mul_f32_e32 v4, v4, v234
	v_mul_f32_e32 v5, v5, v234
	v_mul_f32_e32 v6, v6, v234
	v_mul_f32_e32 v7, v7, v234
	v_mul_f32_e32 v8, v8, v234
	v_mul_f32_e32 v9, v9, v234
	v_mul_f32_e32 v10, v10, v234
	v_mul_f32_e32 v11, v11, v234
	v_mul_f32_e32 v12, v12, v234
	v_mul_f32_e32 v13, v13, v234
	v_mul_f32_e32 v14, v14, v234
	v_mul_f32_e32 v15, v15, v234
.Lat32_nors0f:
	v_pk_add_f32 v[80:81], v[80:81], v[152:153] neg_lo:[0,1] neg_hi:[0,1]
	v_pk_add_f32 v[82:83], v[82:83], v[152:153] neg_lo:[0,1] neg_hi:[0,1]
	v_pk_add_f32 v[84:85], v[84:85], v[152:153] neg_lo:[0,1] neg_hi:[0,1]
	v_pk_add_f32 v[86:87], v[86:87], v[152:153] neg_lo:[0,1] neg_hi:[0,1]
	v_exp_f32_e32 v80, v80
	v_exp_f32_e32 v81, v81
	v_exp_f32_e32 v82, v82
	v_exp_f32_e32 v83, v83
	v_exp_f32_e32 v84, v84
	v_exp_f32_e32 v85, v85
	v_exp_f32_e32 v86, v86
	v_exp_f32_e32 v87, v87
	v_add_f32_e32 v236, v80, v82
	v_add_f32_e32 v237, v81, v83
	v_add_f32_e32 v236, v236, v84
	v_add_f32_e32 v237, v237, v85
	v_add_f32_e32 v236, v236, v86
	v_add_f32_e32 v237, v237, v87
	v_cvt_pk_bf16_f32 v80, v80, v81
	v_cvt_pk_bf16_f32 v81, v82, v83
	v_cvt_pk_bf16_f32 v82, v84, v85
	v_cvt_pk_bf16_f32 v83, v86, v87
	s_waitcnt lgkmcnt(0)
; template <int DK>
; DI void attn_item(const Params& p, int layer, int b, int hd, int qt, int ctxq, char* smem) {
;     ...
;             float mx = x[0][0];
; #pragma unroll
;             for (int i = 1; i < 16; ++i) mx = fmaxf(mx, x[0][i]);
; #pragma unroll
;             for (int i = 0; i < 16; ++i) mx = fmaxf(mx, x[1][i]);
;             mx = fmaxf(mx, shx(mx, lane, 32));
;             if (__builtin_amdgcn_ballot_w64(mx > m_[s] + 8.f) != 0) {
;                 const float mn = fmaxf(m_[s], mx);
;                 const float al = __builtin_amdgcn_exp2f(m_[s] - mn);
;                 m_[s] = mn;
;                 l_[s] *= al;
; #pragma unroll
;                 for (int d = 0; d < 2; ++d)
; #pragma unroll
;                     for (int i = 0; i < 16; ++i) O[s][d][i] *= al;
;             }
;             const f32x2 mref = {m_[s], m_[s]};
;             float ps = 0.f;
; #pragma unroll
;             for (int kb = 0; kb < 2; ++kb)
; #pragma unroll
;                 for (int i2 = 0; i2 < 8; ++i2) {
;                     f32x2 t = {x[kb][2 * i2], x[kb][2 * i2 + 1]};
;                     asm("v_pk_add_f32 %0, %1, %2 neg_lo:[0,1] neg_hi:[0,1]" : "=v"(t) : "v"(t), "v"(mref));
;                     const float e0 = __builtin_amdgcn_exp2f(t.x), e1 = __builtin_amdgcn_exp2f(t.y);
;                     x[kb][2 * i2] = e0; x[kb][2 * i2 + 1] = e1; ps += e0 + e1;
;                 }
;             l_[s] += ps;
; #pragma unroll
;             for (int kb = 0; kb < 2; ++kb)
; #pragma unroll
;                 for (int st = 0; st < 2; ++st) {
;                     u32x4 w;
;                     w.x = pk_bf16(x[kb][8 * st], x[kb][8 * st + 1]); w.y = pk_bf16(x[kb][8 * st + 2], x[kb][8 * st + 3]);
;                     w.z = pk_bf16(x[kb][8 * st + 4], x[kb][8 * st + 5]); w.w = pk_bf16(x[kb][8 * st + 6], x[kb][8 * st + 7]);
;                     const bf16x8 pfr = __builtin_bit_cast(bf16x8, w);
; #pragma unroll
;                     for (int d = 0; d < 2; ++d) {
;                         const bf16_t* vp = vb_ + (32 * d + r) * 68 + 32 * kb + 16 * st + 4 * h;
;                         const s16x4 lo = *(const s16x4*)vp, hi = *(const s16x4*)(vp + 8);
;                         const bf16x8 vf = __builtin_shufflevector(lo, hi, 0, 1, 2, 3, 4, 5, 6, 7);
;                         O[s][d] = MFMA32(vf, pfr, O[s][d]);
;                     }
;                 }
;         }
;         if (kt + 1 < nkt) {
	v_pk_add_f32 v[88:89], v[88:89], v[152:153] neg_lo:[0,1] neg_hi:[0,1]
	v_pk_add_f32 v[90:91], v[90:91], v[152:153] neg_lo:[0,1] neg_hi:[0,1]
	v_pk_add_f32 v[92:93], v[92:93], v[152:153] neg_lo:[0,1] neg_hi:[0,1]
	v_pk_add_f32 v[94:95], v[94:95], v[152:153] neg_lo:[0,1] neg_hi:[0,1]
	v_mfma_f32_32x32x16_bf16 v[32:47], v[96:99], v[80:83], v[32:47]
	v_mfma_f32_32x32x16_bf16 v[0:15], v[112:115], v[80:83], v[0:15]
	v_exp_f32_e32 v88, v88
	v_exp_f32_e32 v89, v89
	v_exp_f32_e32 v90, v90
	v_exp_f32_e32 v91, v91
	v_exp_f32_e32 v92, v92
	v_exp_f32_e32 v93, v93
	v_exp_f32_e32 v94, v94
	v_exp_f32_e32 v95, v95
	v_add_f32_e32 v236, v236, v88
	v_add_f32_e32 v237, v237, v89
	v_add_f32_e32 v236, v236, v90
	v_add_f32_e32 v237, v237, v91
	v_add_f32_e32 v236, v236, v92
	v_add_f32_e32 v237, v237, v93
	v_add_f32_e32 v236, v236, v94
	v_add_f32_e32 v237, v237, v95
	v_cvt_pk_bf16_f32 v88, v88, v89
	v_cvt_pk_bf16_f32 v89, v90, v91
	v_cvt_pk_bf16_f32 v90, v92, v93
	v_cvt_pk_bf16_f32 v91, v94, v95
	v_pk_add_f32 v[64:65], v[64:65], v[152:153] neg_lo:[0,1] neg_hi:[0,1]
	v_pk_add_f32 v[66:67], v[66:67], v[152:153] neg_lo:[0,1] neg_hi:[0,1]
	v_pk_add_f32 v[68:69], v[68:69], v[152:153] neg_lo:[0,1] neg_hi:[0,1]
	v_pk_add_f32 v[70:71], v[70:71], v[152:153] neg_lo:[0,1] neg_hi:[0,1]
	v_mfma_f32_32x32x16_bf16 v[32:47], v[100:103], v[88:91], v[32:47]
	v_mfma_f32_32x32x16_bf16 v[0:15], v[116:119], v[88:91], v[0:15]
	v_mfma_f32_32x32x16_bf16 v[80:95], v[128:131], v[244:247], 0
	v_mfma_f32_32x32x16_bf16 v[80:95], v[136:139], v[248:251], v[80:95]
	v_exp_f32_e32 v64, v64
	v_exp_f32_e32 v65, v65
	v_exp_f32_e32 v66, v66
	v_exp_f32_e32 v67, v67
	v_exp_f32_e32 v68, v68
	v_exp_f32_e32 v69, v69
	v_exp_f32_e32 v70, v70
	v_exp_f32_e32 v71, v71
	v_add_f32_e32 v236, v236, v64
	v_add_f32_e32 v237, v237, v65
	v_add_f32_e32 v236, v236, v66
	v_add_f32_e32 v237, v237, v67
	v_add_f32_e32 v236, v236, v68
	v_add_f32_e32 v237, v237, v69
	v_add_f32_e32 v236, v236, v70
	v_add_f32_e32 v237, v237, v71
	v_cvt_pk_bf16_f32 v64, v64, v65
	v_cvt_pk_bf16_f32 v65, v66, v67
	v_cvt_pk_bf16_f32 v66, v68, v69
	v_cvt_pk_bf16_f32 v67, v70, v71
	v_pk_add_f32 v[72:73], v[72:73], v[152:153] neg_lo:[0,1] neg_hi:[0,1]
	v_pk_add_f32 v[74:75], v[74:75], v[152:153] neg_lo:[0,1] neg_hi:[0,1]
	v_pk_add_f32 v[76:77], v[76:77], v[152:153] neg_lo:[0,1] neg_hi:[0,1]
	v_pk_add_f32 v[78:79], v[78:79], v[152:153] neg_lo:[0,1] neg_hi:[0,1]
	v_mfma_f32_32x32x16_bf16 v[32:47], v[104:107], v[64:67], v[32:47]
	v_mfma_f32_32x32x16_bf16 v[0:15], v[120:123], v[64:67], v[0:15]
	v_exp_f32_e32 v72, v72
	v_exp_f32_e32 v73, v73
	v_exp_f32_e32 v74, v74
	v_exp_f32_e32 v75, v75
	v_exp_f32_e32 v76, v76
	v_exp_f32_e32 v77, v77
	v_exp_f32_e32 v78, v78
	v_exp_f32_e32 v79, v79
	v_add_f32_e32 v236, v236, v72
	v_add_f32_e32 v237, v237, v73
	v_add_f32_e32 v236, v236, v74
	v_add_f32_e32 v237, v237, v75
	v_add_f32_e32 v236, v236, v76
	v_add_f32_e32 v237, v237, v77
	v_add_f32_e32 v236, v236, v78
	v_add_f32_e32 v237, v237, v79
	v_cvt_pk_bf16_f32 v72, v72, v73
	v_cvt_pk_bf16_f32 v73, v74, v75
	v_cvt_pk_bf16_f32 v74, v76, v77
	v_cvt_pk_bf16_f32 v75, v78, v79
	v_add_f32_e32 v236, v236, v237
	v_add_f32_e32 v151, v151, v236
	v_mfma_f32_32x32x16_bf16 v[32:47], v[108:111], v[72:75], v[32:47]
	v_mfma_f32_32x32x16_bf16 v[0:15], v[124:127], v[72:75], v[0:15]
	v_mfma_f32_32x32x16_bf16 v[64:79], v[132:135], v[244:247], 0
	v_mfma_f32_32x32x16_bf16 v[64:79], v[140:143], v[248:251], v[64:79]
	v_sub_f32_e32 v174, 0, v152
	v_sub_f32_e32 v175, 0, v152
	v_sub_f32_e32 v176, 0, v152
	v_sub_f32_e32 v177, 0, v152
	v_sub_f32_e32 v178, 0, v152
	v_sub_f32_e32 v179, 0, v152
	v_sub_f32_e32 v180, 0, v152
	v_sub_f32_e32 v181, 0, v152
	v_sub_f32_e32 v182, 0, v152
	v_sub_f32_e32 v183, 0, v152
	v_sub_f32_e32 v184, 0, v152
	v_sub_f32_e32 v185, 0, v152
	v_sub_f32_e32 v186, 0, v152
	v_sub_f32_e32 v187, 0, v152
	v_sub_f32_e32 v188, 0, v152
	v_sub_f32_e32 v189, 0, v152
	s_xor_b32 s9, s9, 1
	s_mul_i32 s10, s9, 0x2400
	s_mul_i32 s11, s9, 0x2200
	v_add_u32_e32 v233, s10, v148
	v_add_u32_e32 v234, s11, v150
	v_add_u32_e32 v239, 0x5900, v234
	v_add_u32_e32 v234, 0x4800, v234
	v_add_u32_e32 v173, s10, v149
	s_waitcnt vmcnt(0)
	ds_write_b128 v233, v[206:209]
	ds_write_b128 v233, v[210:213] offset:4608
	ds_write2_b64 v234, v[214:215], v[216:217] offset1:1
	ds_write2_b64 v239, v[218:219], v[220:221] offset1:1
	s_mov_b64 s[10:11], 0x80
	v_lshl_add_u64 v[226:227], v[226:227], 0, s[10:11]
	s_mov_b64 s[10:11], 0x2000
	v_lshl_add_u64 v[230:231], v[230:231], 0, s[10:11]
	s_mov_b64 s[10:11], 0x84000
	v_lshl_add_u64 v[236:237], v[226:227], 0, s[10:11]
	global_load_dwordx4 v[206:209], v[230:231], off offset:-4096
	global_load_dwordx4 v[210:213], v[230:231], off
	global_load_dwordx4 v[214:217], v[226:227], off offset:128
	global_load_dwordx4 v[218:221], v[236:237], off offset:128
	v_max3_f32 v233, v80, v81, v82
	v_max3_f32 v233, v233, v83, v84
	v_max3_f32 v233, v233, v85, v86
	v_max3_f32 v233, v233, v87, v88
	v_max3_f32 v233, v233, v89, v90
	v_max3_f32 v233, v233, v91, v92
	v_max3_f32 v233, v233, v93, v94
	v_max3_f32 v234, v64, v65, v66
	v_max_f32_e32 v233, v233, v95
	v_max3_f32 v234, v234, v67, v68
	v_max3_f32 v234, v234, v69, v70
	v_max3_f32 v234, v234, v71, v72
	v_max3_f32 v234, v234, v73, v74
	v_max3_f32 v234, v234, v75, v76
	v_max3_f32 v234, v234, v77, v78
	v_max3_f32 v233, v233, v234, v79
	v_mov_b32_e32 v234, v233
	s_nop 1
	v_permlane32_swap_b32_e32 v234, v233
	s_nop 0
	v_max_f32_e32 v233, v233, v234
	v_add_f32_e32 v234, 0x41000000, v146
	v_cmp_gt_f32_e32 vcc, v233, v234
	s_cbranch_vccz .Lat32_nors1f
	v_max_f32_e32 v239, v146, v233
	v_sub_f32_e32 v234, v146, v239
	v_exp_f32_e32 v234, v234
	v_mov_b32_e32 v146, v239
	v_mov_b32_e32 v147, v239
	v_mul_f32_e32 v170, v170, v234
	v_mul_f32_e32 v48, v48, v234
	v_mul_f32_e32 v49, v49, v234
	v_mul_f32_e32 v50, v50, v234
	v_mul_f32_e32 v51, v51, v234
	v_mul_f32_e32 v52, v52, v234
	v_mul_f32_e32 v53, v53, v234
	v_mul_f32_e32 v54, v54, v234
	v_mul_f32_e32 v55, v55, v234
	v_mul_f32_e32 v56, v56, v234
	v_mul_f32_e32 v57, v57, v234
	v_mul_f32_e32 v58, v58, v234
	v_mul_f32_e32 v59, v59, v234
	v_mul_f32_e32 v60, v60, v234
	v_mul_f32_e32 v61, v61, v234
	v_mul_f32_e32 v62, v62, v234
	v_mul_f32_e32 v63, v63, v234
	v_mul_f32_e32 v16, v16, v234
	v_mul_f32_e32 v17, v17, v234
	v_mul_f32_e32 v18, v18, v234
	v_mul_f32_e32 v19, v19, v234
	v_mul_f32_e32 v20, v20, v234
	v_mul_f32_e32 v21, v21, v234
	v_mul_f32_e32 v22, v22, v234
	v_mul_f32_e32 v23, v23, v234
	v_mul_f32_e32 v24, v24, v234
	v_mul_f32_e32 v25, v25, v234
	v_mul_f32_e32 v26, v26, v234
	v_mul_f32_e32 v27, v27, v234
	v_mul_f32_e32 v28, v28, v234
	v_mul_f32_e32 v29, v29, v234
	v_mul_f32_e32 v30, v30, v234
	v_mul_f32_e32 v31, v31, v234

; #define MFMA32(a, b, c) __builtin_amdgcn_mfma_f32_32x32x16_bf16((a), (b), (c), 0, 0, 0)
; DI float shx(float v, int lane, int m) { return __int_as_float(__builtin_amdgcn_ds_bpermute((lane ^ m) << 2, __float_as_int(v))); }
; template <int DK>
; DI void attn_item(const Params& p, int layer, int b, int hd, int qt, int ctxq, char* smem) {
;     ...
;             f32x16 x[2];
; #pragma unroll
;             for (int kb = 0; kb < 2; ++kb)
; #pragma unroll
;                 for (int i = 0; i < 16; ++i) x[kb][i] = 0.f;
;             const int kofs = DK == 32 ? 32 * s : 0;
; #pragma unroll
;             for (int ks = 0; ks < NKS; ++ks) {
;                 const bf16x8 a0 = *(const bf16x8*)(kb_ + r * 72 + kofs + 16 * ks + 8 * h), a1 = *(const bf16x8*)(kb_ + (32 + r) * 72 + kofs + 16 * ks + 8 * h);
;                 const bf16x8 qv = *(const bf16x8*)(sQ + ((s * NKS + ks) * 64 + lane) * 8);
;                 x[0] = MFMA32(a0, qv, x[0]); x[1] = MFMA32(a1, qv, x[1]);
;             }
;             float mx = x[0][0];
; #pragma unroll
;             for (int i = 1; i < 16; ++i) mx = fmaxf(mx, x[0][i]);
; #pragma unroll
;             for (int i = 0; i < 16; ++i) mx = fmaxf(mx, x[1][i]);
;             mx = fmaxf(mx, shx(mx, lane, 32));
;             if (__builtin_amdgcn_ballot_w64(mx > m_[s] + 8.f) != 0) {
;                 const float mn = fmaxf(m_[s], mx);
;                 const float al = __builtin_amdgcn_exp2f(m_[s] - mn);
;                 m_[s] = mn;
;                 l_[s] *= al;
; #pragma unroll
;                 for (int d = 0; d < 2; ++d)
; #pragma unroll
;                     for (int i = 0; i < 16; ++i) O[s][d][i] *= al;
;             }
.Lat32_loop:
	s_and_b32 s9, s8, 1
	s_mul_i32 s10, s9, 0x2400
	s_mul_i32 s11, s9, 0x2200
	v_add_u32_e32 v173, s10, v149
	v_add_u32_e32 v236, s11, v172
	v_add_u32_e32 v237, 0x5800, v236
	v_add_u32_e32 v236, 0x4800, v236
	s_waitcnt lgkmcnt(0)
	v_mfma_f32_32x32x16_bf16 v[80:95], v[128:131], v[222:225], v[174:189]
	v_mfma_f32_32x32x16_bf16 v[80:95], v[136:139], v[240:243], v[80:95]
	v_mfma_f32_32x32x16_bf16 v[64:79], v[132:135], v[222:225], v[174:189]
	v_mfma_f32_32x32x16_bf16 v[64:79], v[140:143], v[240:243], v[64:79]
	ds_read2_b64 v[96:99], v236 offset0:0 offset1:2
	ds_read2_b64 v[112:115], v237 offset0:32 offset1:34
	ds_read2_b64 v[100:103], v236 offset0:4 offset1:6
	ds_read2_b64 v[116:119], v237 offset0:36 offset1:38
	ds_read2_b64 v[104:107], v236 offset0:8 offset1:10
	ds_read2_b64 v[120:123], v237 offset0:40 offset1:42
	ds_read2_b64 v[108:111], v236 offset0:12 offset1:14
	ds_read2_b64 v[124:127], v237 offset0:44 offset1:46
	ds_read_b128 v[128:131], v173 offset:64
	ds_read_b128 v[132:135], v173 offset:4672
	ds_read_b128 v[136:139], v173 offset:96
	ds_read_b128 v[140:143], v173 offset:4704
	v_max3_f32 v233, v80, v81, v82
	v_max3_f32 v233, v233, v83, v84
	v_max3_f32 v233, v233, v85, v86
	v_max3_f32 v233, v233, v87, v88
	v_max3_f32 v233, v233, v89, v90
	v_max3_f32 v233, v233, v91, v92
	v_max3_f32 v233, v233, v93, v94
	v_max3_f32 v234, v64, v65, v66
	v_max_f32_e32 v233, v233, v95
	v_max3_f32 v234, v234, v67, v68
	v_max3_f32 v234, v234, v69, v70
	v_max3_f32 v234, v234, v71, v72
	v_max3_f32 v234, v234, v73, v74
	v_max3_f32 v234, v234, v75, v76
	v_max3_f32 v234, v234, v77, v78
	v_max3_f32 v233, v233, v234, v79
	v_mov_b32_e32 v234, v233
	s_nop 1
	v_permlane32_swap_b32_e32 v234, v233
	s_nop 0
	v_max_f32_e32 v233, v233, v234
	v_cmp_lt_f32_e32 vcc, 0x41000000, v233
	s_cbranch_vccz .Lat32_nors0
	v_max_f32_e32 v239, 0, v233
	v_sub_f32_e32 v234, 0, v239
	v_exp_f32_e32 v234, v234
	v_add_f32_e32 v152, v152, v239
	v_mov_b32_e32 v153, v152
	v_mul_f32_e32 v151, v151, v234
	v_sub_f32_e32 v80, v80, v239
	v_sub_f32_e32 v81, v81, v239
	v_sub_f32_e32 v82, v82, v239
	v_sub_f32_e32 v83, v83, v239
	v_sub_f32_e32 v84, v84, v239
	v_sub_f32_e32 v85, v85, v239
	v_sub_f32_e32 v86, v86, v239
	v_sub_f32_e32 v87, v87, v239
	v_sub_f32_e32 v88, v88, v239
	v_sub_f32_e32 v89, v89, v239
	v_sub_f32_e32 v90, v90, v239
	v_sub_f32_e32 v91, v91, v239
	v_sub_f32_e32 v92, v92, v239
	v_sub_f32_e32 v93, v93, v239
	v_sub_f32_e32 v94, v94, v239
	v_sub_f32_e32 v95, v95, v239
	v_sub_f32_e32 v64, v64, v239
	v_sub_f32_e32 v65, v65, v239
	v_sub_f32_e32 v66, v66, v239
	v_sub_f32_e32 v67, v67, v239
	v_sub_f32_e32 v68, v68, v239
	v_sub_f32_e32 v69, v69, v239
	v_sub_f32_e32 v70, v70, v239
	v_sub_f32_e32 v71, v71, v239
	v_sub_f32_e32 v72, v72, v239
	v_sub_f32_e32 v73, v73, v239
	v_sub_f32_e32 v74, v74, v239
	v_sub_f32_e32 v75, v75, v239
	v_sub_f32_e32 v76, v76, v239
	v_sub_f32_e32 v77, v77, v239
	v_sub_f32_e32 v78, v78, v239
	v_sub_f32_e32 v79, v79, v239
	v_sub_f32_e32 v174, 0, v152
	v_sub_f32_e32 v175, 0, v152
	v_sub_f32_e32 v176, 0, v152
	v_sub_f32_e32 v177, 0, v152
	v_sub_f32_e32 v178, 0, v152
	v_sub_f32_e32 v179, 0, v152
	v_sub_f32_e32 v180, 0, v152
	v_sub_f32_e32 v181, 0, v152
	v_sub_f32_e32 v182, 0, v152
	v_sub_f32_e32 v183, 0, v152
	v_sub_f32_e32 v184, 0, v152
	v_sub_f32_e32 v185, 0, v152
	v_sub_f32_e32 v186, 0, v152
	v_sub_f32_e32 v187, 0, v152
	v_sub_f32_e32 v188, 0, v152
	v_sub_f32_e32 v189, 0, v152
	v_mul_f32_e32 v32, v32, v234
	v_mul_f32_e32 v33, v33, v234
	v_mul_f32_e32 v34, v34, v234
	v_mul_f32_e32 v35, v35, v234
	v_mul_f32_e32 v36, v36, v234
	v_mul_f32_e32 v37, v37, v234
	v_mul_f32_e32 v38, v38, v234
	v_mul_f32_e32 v39, v39, v234
	v_mul_f32_e32 v40, v40, v234
	v_mul_f32_e32 v41, v41, v234
	v_mul_f32_e32 v42, v42, v234
	v_mul_f32_e32 v43, v43, v234
	v_mul_f32_e32 v44, v44, v234
	v_mul_f32_e32 v45, v45, v234
	v_mul_f32_e32 v46, v46, v234
	v_mul_f32_e32 v47, v47, v234
	v_mul_f32_e32 v0, v0, v234
	v_mul_f32_e32 v1, v1, v234
	v_mul_f32_e32 v2, v2, v234
	v_mul_f32_e32 v3, v3, v234
	v_mul_f32_e32 v4, v4, v234
	v_mul_f32_e32 v5, v5, v234
	v_mul_f32_e32 v6, v6, v234
	v_mul_f32_e32 v7, v7, v234
	v_mul_f32_e32 v8, v8, v234
	v_mul_f32_e32 v9, v9, v234
	v_mul_f32_e32 v10, v10, v234
	v_mul_f32_e32 v11, v11, v234
	v_mul_f32_e32 v12, v12, v234
	v_mul_f32_e32 v13, v13, v234
	v_mul_f32_e32 v14, v14, v234
	v_mul_f32_e32 v15, v15, v234
; #define MFMA32(a, b, c) __builtin_amdgcn_mfma_f32_32x32x16_bf16((a), (b), (c), 0, 0, 0)
; DI unsigned pk_bf16(float a, float b) { f32x2 v = {a, b}; bf16v2 r = __builtin_convertvector(v, bf16v2); return __builtin_bit_cast(unsigned, r); }
; template <int DK>
; DI void attn_item(const Params& p, int layer, int b, int hd, int qt, int ctxq, char* smem) {
;     ...
;             const f32x2 mref = {m_[s], m_[s]};
;             float ps = 0.f;
; #pragma unroll
;             for (int kb = 0; kb < 2; ++kb)
; #pragma unroll
;                 for (int i2 = 0; i2 < 8; ++i2) {
;                     f32x2 t = {x[kb][2 * i2], x[kb][2 * i2 + 1]};
;                     asm("v_pk_add_f32 %0, %1, %2 neg_lo:[0,1] neg_hi:[0,1]" : "=v"(t) : "v"(t), "v"(mref));
;                     const float e0 = __builtin_amdgcn_exp2f(t.x), e1 = __builtin_amdgcn_exp2f(t.y);
;                     x[kb][2 * i2] = e0; x[kb][2 * i2 + 1] = e1; ps += e0 + e1;
;                 }
;             l_[s] += ps;
; #pragma unroll
;             for (int kb = 0; kb < 2; ++kb)
; #pragma unroll
;                 for (int st = 0; st < 2; ++st) {
;                     u32x4 w;
;                     w.x = pk_bf16(x[kb][8 * st], x[kb][8 * st + 1]); w.y = pk_bf16(x[kb][8 * st + 2], x[kb][8 * st + 3]);
;                     w.z = pk_bf16(x[kb][8 * st + 4], x[kb][8 * st + 5]); w.w = pk_bf16(x[kb][8 * st + 6], x[kb][8 * st + 7]);
;                     const bf16x8 pfr = __builtin_bit_cast(bf16x8, w);
; #pragma unroll
;                     for (int d = 0; d < 2; ++d) {
;                         const bf16_t* vp = vb_ + (32 * d + r) * 68 + 32 * kb + 16 * st + 4 * h;
;                         const s16x4 lo = *(const s16x4*)vp, hi = *(const s16x4*)(vp + 8);
;                         const bf16x8 vf = __builtin_shufflevector(lo, hi, 0, 1, 2, 3, 4, 5, 6, 7);
;                         O[s][d] = MFMA32(vf, pfr, O[s][d]);
;                     }
;                 }
;         }
;         if (kt + 1 < nkt) {
;             bf16_t* wk = sK + (cur ^ 1) * 64 * 72; bf16_t* wv = sV + (cur ^ 1) * 64 * 68;
; #pragma unroll
;             for (int i = 0; i < 2; ++i) {
;                 *(u32x4*)(wk + (srow + 32 * i) * 72 + sc8) = rk[i];
;                 *(u32x2*)(wv + (srow + 32 * i) * 68 + sc8) = (u32x2){rv[i].x, rv[i].y}; *(u32x2*)(wv + (srow + 32 * i) * 68 + sc8 + 4) = (u32x2){rv[i].z, rv[i].w};
;             }
;         }
.Lat32_nors0:
	v_exp_f32_e32 v80, v80
	v_exp_f32_e32 v81, v81
	v_exp_f32_e32 v82, v82
	v_exp_f32_e32 v83, v83
	v_exp_f32_e32 v84, v84
	v_exp_f32_e32 v85, v85
	v_exp_f32_e32 v86, v86
	v_exp_f32_e32 v87, v87
	v_add_f32_e32 v236, v80, v82
	v_add_f32_e32 v237, v81, v83
	v_add_f32_e32 v236, v236, v84
	v_add_f32_e32 v237, v237, v85
	v_add_f32_e32 v236, v236, v86
	v_add_f32_e32 v237, v237, v87
	v_cvt_pk_bf16_f32 v80, v80, v81
	v_cvt_pk_bf16_f32 v81, v82, v83
	v_cvt_pk_bf16_f32 v82, v84, v85
	v_cvt_pk_bf16_f32 v83, v86, v87
	s_waitcnt lgkmcnt(0)
	v_exp_f32_e32 v88, v88
	v_exp_f32_e32 v89, v89
	v_mfma_f32_32x32x16_bf16 v[32:47], v[96:99], v[80:83], v[32:47]
	v_mfma_f32_32x32x16_bf16 v[0:15], v[112:115], v[80:83], v[0:15]
	v_exp_f32_e32 v90, v90
	v_exp_f32_e32 v91, v91
	v_exp_f32_e32 v92, v92
	v_exp_f32_e32 v93, v93
	v_exp_f32_e32 v94, v94
	v_exp_f32_e32 v95, v95
	v_add_f32_e32 v236, v236, v88
	v_add_f32_e32 v237, v237, v89
	v_add_f32_e32 v236, v236, v90
	v_add_f32_e32 v237, v237, v91
	v_add_f32_e32 v236, v236, v92
	v_add_f32_e32 v237, v237, v93
	v_add_f32_e32 v236, v236, v94
	v_add_f32_e32 v237, v237, v95
	v_cvt_pk_bf16_f32 v88, v88, v89
	v_cvt_pk_bf16_f32 v89, v90, v91
	v_cvt_pk_bf16_f32 v90, v92, v93
	v_cvt_pk_bf16_f32 v91, v94, v95
	v_exp_f32_e32 v64, v64
	v_exp_f32_e32 v65, v65
	v_mfma_f32_32x32x16_bf16 v[32:47], v[100:103], v[88:91], v[32:47]
	v_mfma_f32_32x32x16_bf16 v[0:15], v[116:119], v[88:91], v[0:15]
	v_mfma_f32_32x32x16_bf16 v[80:95], v[128:131], v[244:247], v[190:205]
	v_mfma_f32_32x32x16_bf16 v[80:95], v[136:139], v[248:251], v[80:95]
	v_exp_f32_e32 v66, v66
	v_exp_f32_e32 v67, v67
	v_exp_f32_e32 v68, v68
	v_exp_f32_e32 v69, v69
	v_exp_f32_e32 v70, v70
	v_exp_f32_e32 v71, v71
	v_add_f32_e32 v236, v236, v64
	v_add_f32_e32 v237, v237, v65
	v_add_f32_e32 v236, v236, v66
	v_add_f32_e32 v237, v237, v67
	v_add_f32_e32 v236, v236, v68
	v_add_f32_e32 v237, v237, v69
	v_add_f32_e32 v236, v236, v70
	v_add_f32_e32 v237, v237, v71
	v_cvt_pk_bf16_f32 v64, v64, v65
	v_cvt_pk_bf16_f32 v65, v66, v67
	v_cvt_pk_bf16_f32 v66, v68, v69
	v_cvt_pk_bf16_f32 v67, v70, v71
	v_exp_f32_e32 v72, v72
	v_exp_f32_e32 v73, v73
	v_mfma_f32_32x32x16_bf16 v[32:47], v[104:107], v[64:67], v[32:47]
	v_mfma_f32_32x32x16_bf16 v[0:15], v[120:123], v[64:67], v[0:15]
	v_exp_f32_e32 v74, v74
	v_exp_f32_e32 v75, v75
	v_exp_f32_e32 v76, v76
	v_exp_f32_e32 v77, v77
	v_exp_f32_e32 v78, v78
	v_exp_f32_e32 v79, v79
	v_add_f32_e32 v236, v236, v72
	v_add_f32_e32 v237, v237, v73
	v_add_f32_e32 v236, v236, v74
	v_add_f32_e32 v237, v237, v75
	v_add_f32_e32 v236, v236, v76
	v_add_f32_e32 v237, v237, v77
	v_add_f32_e32 v236, v236, v78
	v_add_f32_e32 v237, v237, v79
	v_cvt_pk_bf16_f32 v72, v72, v73
	v_cvt_pk_bf16_f32 v73, v74, v75
	v_cvt_pk_bf16_f32 v74, v76, v77
	v_cvt_pk_bf16_f32 v75, v78, v79
	v_add_f32_e32 v236, v236, v237
	v_add_f32_e32 v151, v151, v236
	v_mfma_f32_32x32x16_bf16 v[32:47], v[108:111], v[72:75], v[32:47]
	v_mfma_f32_32x32x16_bf16 v[0:15], v[124:127], v[72:75], v[0:15]
	v_mfma_f32_32x32x16_bf16 v[64:79], v[132:135], v[244:247], v[190:205]
	v_mfma_f32_32x32x16_bf16 v[64:79], v[140:143], v[248:251], v[64:79]
	s_xor_b32 s9, s9, 1
	s_mul_i32 s10, s9, 0x2400
	s_mul_i32 s11, s9, 0x2200
	v_add_u32_e32 v233, s10, v148
	v_add_u32_e32 v234, s11, v150
	v_add_u32_e32 v239, 0x5900, v234
	v_add_u32_e32 v234, 0x4800, v234
	v_add_u32_e32 v173, s10, v149
	s_waitcnt vmcnt(0)
	ds_write_b128 v233, v[206:209]
	ds_write_b128 v233, v[210:213] offset:4608
	ds_write2_b64 v234, v[214:215], v[216:217] offset1:1
	ds_write2_b64 v239, v[218:219], v[220:221] offset1:1
	s_cmp_lt_u32 s8, 0x82
	s_cbranch_scc0 .Lat32_skipld
	s_mov_b64 s[10:11], 0x80
	v_lshl_add_u64 v[226:227], v[226:227], 0, s[10:11]
	s_mov_b64 s[10:11], 0x2000
	v_lshl_add_u64 v[230:231], v[230:231], 0, s[10:11]
	s_mov_b64 s[10:11], 0x84000
	v_lshl_add_u64 v[236:237], v[226:227], 0, s[10:11]
	global_load_dwordx4 v[206:209], v[230:231], off offset:-4096
	global_load_dwordx4 v[210:213], v[230:231], off
	global_load_dwordx4 v[214:217], v[226:227], off offset:128
	global_load_dwordx4 v[218:221], v[236:237], off offset:128
; template <int DK>
; DI void attn_item(const Params& p, int layer, int b, int hd, int qt, int ctxq, char* smem) {
;     ...
;             float mx = x[0][0];
; #pragma unroll
;             for (int i = 1; i < 16; ++i) mx = fmaxf(mx, x[0][i]);
; #pragma unroll
;             for (int i = 0; i < 16; ++i) mx = fmaxf(mx, x[1][i]);
;             mx = fmaxf(mx, shx(mx, lane, 32));
;             if (__builtin_amdgcn_ballot_w64(mx > m_[s] + 8.f) != 0) {
;                 const float mn = fmaxf(m_[s], mx);
;                 const float al = __builtin_amdgcn_exp2f(m_[s] - mn);
;                 m_[s] = mn;
;                 l_[s] *= al;
; #pragma unroll
;                 for (int d = 0; d < 2; ++d)
; #pragma unroll
;                     for (int i = 0; i < 16; ++i) O[s][d][i] *= al;
;             }
;             const f32x2 mref = {m_[s], m_[s]};
;             float ps = 0.f;
; #pragma unroll
;             for (int kb = 0; kb < 2; ++kb)
; #pragma unroll
;                 for (int i2 = 0; i2 < 8; ++i2) {
;                     f32x2 t = {x[kb][2 * i2], x[kb][2 * i2 + 1]};
;                     asm("v_pk_add_f32 %0, %1, %2 neg_lo:[0,1] neg_hi:[0,1]" : "=v"(t) : "v"(t), "v"(mref));
;                     const float e0 = __builtin_amdgcn_exp2f(t.x), e1 = __builtin_amdgcn_exp2f(t.y);
;                     x[kb][2 * i2] = e0; x[kb][2 * i2 + 1] = e1; ps += e0 + e1;
;                 }
;             l_[s] += ps;
; #pragma unroll
;             for (int kb = 0; kb < 2; ++kb)
; #pragma unroll
;                 for (int st = 0; st < 2; ++st) {
;                     u32x4 w;
;                     w.x = pk_bf16(x[kb][8 * st], x[kb][8 * st + 1]); w.y = pk_bf16(x[kb][8 * st + 2], x[kb][8 * st + 3]);
;                     w.z = pk_bf16(x[kb][8 * st + 4], x[kb][8 * st + 5]); w.w = pk_bf16(x[kb][8 * st + 6], x[kb][8 * st + 7]);
;                     const bf16x8 pfr = __builtin_bit_cast(bf16x8, w);
; #pragma unroll
;                     for (int d = 0; d < 2; ++d) {
;                         const bf16_t* vp = vb_ + (32 * d + r) * 68 + 32 * kb + 16 * st + 4 * h;
;                         const s16x4 lo = *(const s16x4*)vp, hi = *(const s16x4*)(vp + 8);
;                         const bf16x8 vf = __builtin_shufflevector(lo, hi, 0, 1, 2, 3, 4, 5, 6, 7);
;                         O[s][d] = MFMA32(vf, pfr, O[s][d]);
;                     }
;                 }
;         }
;         if (kt + 1 < nkt) {
.Lat32_skipld:
	v_max3_f32 v233, v80, v81, v82
	v_max3_f32 v233, v233, v83, v84
	v_max3_f32 v233, v233, v85, v86
	v_max3_f32 v233, v233, v87, v88
	v_max3_f32 v233, v233, v89, v90
	v_max3_f32 v233, v233, v91, v92
	v_max3_f32 v233, v233, v93, v94
	v_max3_f32 v234, v64, v65, v66
	v_max_f32_e32 v233, v233, v95
	v_max3_f32 v234, v234, v67, v68
	v_max3_f32 v234, v234, v69, v70
	v_max3_f32 v234, v234, v71, v72
	v_max3_f32 v234, v234, v73, v74
	v_max3_f32 v234, v234, v75, v76
	v_max3_f32 v234, v234, v77, v78
	v_max3_f32 v233, v233, v234, v79
	v_mov_b32_e32 v234, v233
	s_nop 1
	v_permlane32_swap_b32_e32 v234, v233
	s_nop 0
	v_max_f32_e32 v233, v233, v234
	v_cmp_lt_f32_e32 vcc, 0x41000000, v233
	s_cbranch_vccz .Lat32_nors1
	v_max_f32_e32 v239, 0, v233
	v_sub_f32_e32 v234, 0, v239
	v_exp_f32_e32 v234, v234
	v_add_f32_e32 v146, v146, v239
	v_mov_b32_e32 v147, v146
	v_mul_f32_e32 v170, v170, v234
	v_sub_f32_e32 v80, v80, v239
	v_sub_f32_e32 v81, v81, v239
	v_sub_f32_e32 v82, v82, v239
	v_sub_f32_e32 v83, v83, v239
	v_sub_f32_e32 v84, v84, v239
	v_sub_f32_e32 v85, v85, v239
	v_sub_f32_e32 v86, v86, v239
	v_sub_f32_e32 v87, v87, v239
	v_sub_f32_e32 v88, v88, v239
	v_sub_f32_e32 v89, v89, v239
	v_sub_f32_e32 v90, v90, v239
	v_sub_f32_e32 v91, v91, v239
	v_sub_f32_e32 v92, v92, v239
	v_sub_f32_e32 v93, v93, v239
	v_sub_f32_e32 v94, v94, v239
	v_sub_f32_e32 v95, v95, v239
	v_sub_f32_e32 v64, v64, v239
	v_sub_f32_e32 v65, v65, v239
	v_sub_f32_e32 v66, v66, v239
	v_sub_f32_e32 v67, v67, v239
	v_sub_f32_e32 v68, v68, v239
	v_sub_f32_e32 v69, v69, v239
	v_sub_f32_e32 v70, v70, v239
	v_sub_f32_e32 v71, v71, v239
	v_sub_f32_e32 v72, v72, v239
	v_sub_f32_e32 v73, v73, v239
	v_sub_f32_e32 v74, v74, v239
	v_sub_f32_e32 v75, v75, v239
	v_sub_f32_e32 v76, v76, v239
	v_sub_f32_e32 v77, v77, v239
	v_sub_f32_e32 v78, v78, v239
	v_sub_f32_e32 v79, v79, v239
	v_sub_f32_e32 v190, 0, v146
	v_sub_f32_e32 v191, 0, v146
	v_sub_f32_e32 v192, 0, v146
	v_sub_f32_e32 v193, 0, v146
	v_sub_f32_e32 v194, 0, v146
	v_sub_f32_e32 v195, 0, v146
	v_sub_f32_e32 v196, 0, v146
	v_sub_f32_e32 v197, 0, v146
	v_sub_f32_e32 v198, 0, v146
	v_sub_f32_e32 v199, 0, v146
	v_sub_f32_e32 v200, 0, v146
	v_sub_f32_e32 v201, 0, v146
	v_sub_f32_e32 v202, 0, v146
	v_sub_f32_e32 v203, 0, v146
	v_sub_f32_e32 v204, 0, v146
	v_sub_f32_e32 v205, 0, v146
	v_mul_f32_e32 v48, v48, v234
	v_mul_f32_e32 v49, v49, v234
	v_mul_f32_e32 v50, v50, v234
	v_mul_f32_e32 v51, v51, v234
	v_mul_f32_e32 v52, v52, v234
	v_mul_f32_e32 v53, v53, v234
	v_mul_f32_e32 v54, v54, v234
	v_mul_f32_e32 v55, v55, v234
	v_mul_f32_e32 v56, v56, v234
	v_mul_f32_e32 v57, v57, v234
	v_mul_f32_e32 v58, v58, v234
	v_mul_f32_e32 v59, v59, v234
	v_mul_f32_e32 v60, v60, v234
	v_mul_f32_e32 v61, v61, v234
	v_mul_f32_e32 v62, v62, v234
	v_mul_f32_e32 v63, v63, v234
	v_mul_f32_e32 v16, v16, v234
	v_mul_f32_e32 v17, v17, v234
	v_mul_f32_e32 v18, v18, v234
	v_mul_f32_e32 v19, v19, v234
	v_mul_f32_e32 v20, v20, v234
	v_mul_f32_e32 v21, v21, v234
	v_mul_f32_e32 v22, v22, v234
	v_mul_f32_e32 v23, v23, v234
	v_mul_f32_e32 v24, v24, v234
	v_mul_f32_e32 v25, v25, v234
	v_mul_f32_e32 v26, v26, v234
	v_mul_f32_e32 v27, v27, v234
	v_mul_f32_e32 v28, v28, v234
	v_mul_f32_e32 v29, v29, v234
	v_mul_f32_e32 v30, v30, v234
	v_mul_f32_e32 v31, v31, v234
.Lat32_nors1:
	v_exp_f32_e32 v80, v80
	v_exp_f32_e32 v81, v81
	v_exp_f32_e32 v82, v82
	v_exp_f32_e32 v83, v83
	v_exp_f32_e32 v84, v84
	v_exp_f32_e32 v85, v85
	v_exp_f32_e32 v86, v86
	v_exp_f32_e32 v87, v87
	v_add_f32_e32 v236, v80, v82
	v_add_f32_e32 v237, v81, v83
	v_add_f32_e32 v236, v236, v84
	v_add_f32_e32 v237, v237, v85
	v_add_f32_e32 v236, v236, v86
	v_add_f32_e32 v237, v237, v87
	v_cvt_pk_bf16_f32 v80, v80, v81
	v_cvt_pk_bf16_f32 v81, v82, v83
	v_cvt_pk_bf16_f32 v82, v84, v85
	v_cvt_pk_bf16_f32 v83, v86, v87
	v_exp_f32_e32 v88, v88
	v_exp_f32_e32 v89, v89
	v_mfma_f32_32x32x16_bf16 v[48:63], v[96:99], v[80:83], v[48:63]
	v_mfma_f32_32x32x16_bf16 v[16:31], v[112:115], v[80:83], v[16:31]
	v_exp_f32_e32 v90, v90
	v_exp_f32_e32 v91, v91
	v_exp_f32_e32 v92, v92
	v_exp_f32_e32 v93, v93
	v_exp_f32_e32 v94, v94
	v_exp_f32_e32 v95, v95
	v_add_f32_e32 v236, v236, v88
	v_add_f32_e32 v237, v237, v89
	v_add_f32_e32 v236, v236, v90
	v_add_f32_e32 v237, v237, v91
	v_add_f32_e32 v236, v236, v92
	v_add_f32_e32 v237, v237, v93
	v_add_f32_e32 v236, v236, v94
	v_add_f32_e32 v237, v237, v95
	v_cvt_pk_bf16_f32 v88, v88, v89
	v_cvt_pk_bf16_f32 v89, v90, v91
	v_cvt_pk_bf16_f32 v90, v92, v93
	v_cvt_pk_bf16_f32 v91, v94, v95
	v_exp_f32_e32 v64, v64
	v_exp_f32_e32 v65, v65
	v_mfma_f32_32x32x16_bf16 v[48:63], v[100:103], v[88:91], v[48:63]
	v_mfma_f32_32x32x16_bf16 v[16:31], v[116:119], v[88:91], v[16:31]
	s_waitcnt lgkmcnt(0)
	s_barrier
	ds_read_b128 v[128:131], v173
	ds_read_b128 v[132:135], v173 offset:4608
	ds_read_b128 v[136:139], v173 offset:32
	ds_read_b128 v[140:143], v173 offset:4640
	v_exp_f32_e32 v66, v66
	v_exp_f32_e32 v67, v67
	v_exp_f32_e32 v68, v68
	v_exp_f32_e32 v69, v69
	v_exp_f32_e32 v70, v70
	v_exp_f32_e32 v71, v71
	v_add_f32_e32 v236, v236, v64
	v_add_f32_e32 v237, v237, v65
	v_add_f32_e32 v236, v236, v66
	v_add_f32_e32 v237, v237, v67
	v_add_f32_e32 v236, v236, v68
	v_add_f32_e32 v237, v237, v69
	v_add_f32_e32 v236, v236, v70
	v_add_f32_e32 v237, v237, v71
	v_cvt_pk_bf16_f32 v64, v64, v65
	v_cvt_pk_bf16_f32 v65, v66, v67
	v_cvt_pk_bf16_f32 v66, v68, v69
	v_cvt_pk_bf16_f32 v67, v70, v71
	v_exp_f32_e32 v72, v72
	v_exp_f32_e32 v73, v73
	v_mfma_f32_32x32x16_bf16 v[48:63], v[104:107], v[64:67], v[48:63]
	v_mfma_f32_32x32x16_bf16 v[16:31], v[120:123], v[64:67], v[16:31]
	v_exp_f32_e32 v74, v74
	v_exp_f32_e32 v75, v75
	v_exp_f32_e32 v76, v76
	v_exp_f32_e32 v77, v77
	v_exp_f32_e32 v78, v78
	v_exp_f32_e32 v79, v79
	v_add_f32_e32 v236, v236, v72
	v_add_f32_e32 v237, v237, v73
	v_add_f32_e32 v236, v236, v74
	v_add_f32_e32 v237, v237, v75
	v_add_f32_e32 v236, v236, v76
	v_add_f32_e32 v237, v237, v77
	v_add_f32_e32 v236, v236, v78
	v_add_f32_e32 v237, v237, v79
	v_cvt_pk_bf16_f32 v72, v72, v73
	v_cvt_pk_bf16_f32 v73, v74, v75
	v_cvt_pk_bf16_f32 v74, v76, v77
	v_cvt_pk_bf16_f32 v75, v78, v79
	v_add_f32_e32 v236, v236, v237
	v_add_f32_e32 v170, v170, v236
	v_mfma_f32_32x32x16_bf16 v[48:63], v[108:111], v[72:75], v[48:63]
	v_mfma_f32_32x32x16_bf16 v[16:31], v[124:127], v[72:75], v[16:31]
	s_add_i32 s8, s8, 1
	s_cmpk_eq_i32 s8, 0x83
	s_cbranch_scc0 .Lat32_loop
	s_waitcnt lgkmcnt(0)
